# idx unit prologue: first k_idx tile DMA issued right behind the q-tile loads (before their wait) instead of after the staging barrier
# speedup vs baseline: 1.0007x; 1.0007x over previous
; #define LAS __attribute__((address_space(3)))
; #define IDX_DMA_K(zo) do { _Pragma("unroll") for (int d0_ = 0; d0_ < 4; ++d0_) attn_body::glds16(kbh + (zo) + d0_ * 16, (unsigned)__builtin_amdgcn_readfirstlane(kdst + d0_ * 1024)); } while (0)
; __device__ __forceinline__ void run(Frame& F, int qword) {
;     ...
;         for (int it = 0; it < 2; ++it) { const int rem = tid + 512 * it, row = rem >> 5, ch = rem & 31;
;             const v4u v = *(const v4u*)(QIH + (tok0 + row) * 256 + ch * 8);
;             *(LAS v4u*)(lds + row * QROW + ch * 16) = v; }
;         const f32x4 w4 = *(const f32x4*)(WI + (tok0 + r32) * 4);
;         __syncthreads();
;         unsigned sc[8][16];
;         const bf16* kbh = KIH + ((size_t)b * SEQ + r32) * 64 + hi * 8;
;         const LAS unsigned char* kbuf = lds + KBUF_OFF + wid * 8192 + lane * 16;
;         const unsigned kdst = (unsigned)(uintptr_t)(lds + KBUF_OFF + wid * 8192);
;     ...
;         if (widv <= qg) { int zoff = widv * 2048; asm volatile("" : "+v"(zoff)); IDX_DMA_K(zoff); }
;         const int cl = r32 - 4 * hi;
;         const LAS unsigned char* qimg = lds + r32 * QROW + hi * 16;
; #pragma unroll
;         for (int i = 0; i < 8; ++i) {
;             const int kt = widv + 8 * i;
;             if (kt <= qg) {
;                 bf16x8 kh[4];
;                 asm volatile("s_waitcnt vmcnt(0)" ::: "memory");
; #pragma unroll
;                 for (int d0 = 0; d0 < 4; ++d0) kh[d0] = *(const LAS bf16x8*)(kbuf + d0 * 1024);
;                 asm volatile("s_waitcnt lgkmcnt(0)" ::: "memory");
;                 if (kt + 8 <= qg) { int zoff = (kt + 8) * 2048; asm volatile("" : "+v"(zoff)); IDX_DMA_K(zoff); }
.LBB0_956:
	s_waitcnt lgkmcnt(0)
	s_barrier
	ds_read_b32 v0, v134
	s_mov_b64 s[0:1], -1
	s_waitcnt lgkmcnt(0)
	v_readfirstlane_b32 s4, v0
	s_cmpk_gt_u32 s4, 0x3ff
	s_cbranch_scc1 .LBB0_949
	v_sub_co_u32_e32 v0, vcc, s4, v135
	s_lshr_b32 s0, s4, 4
	s_sub_i32 s5, 63, s0
	v_readfirstlane_b32 s0, v0
	s_lshr_b32 s6, s0, 4
	s_and_b64 s[0:1], vcc, exec
	s_cselect_b32 s61, s5, s6
	s_and_b32 s4, s4, 15
	s_lshl_b32 s0, s4, 6
	s_add_i32 s34, s61, s0
	s_lshl_b64 s[0:1], s[34:35], 13
	s_add_u32 s38, s46, s0
	v_mbcnt_lo_u32_b32 v136, -1, 0
	v_mbcnt_hi_u32_b32 v136, -1, v136
	s_addc_u32 s39, s47, s1
	s_or_b32 s63, s61, 7
	s_mov_b32 s62, s93
	v_and_b32_e32 v137, 31, v136
	s_cmp_lt_u32 s61, 8
	s_mov_b64 s[0:1], -1
	s_cbranch_scc1 .LBB0_1290
	v_add_u32_e32 v4, s48, v136
	v_ashrrev_i32_e32 v10, 5, v4
	v_add_u32_e32 v4, 0x200, v4
	s_lshl_b32 s12, s61, 5
	s_lshl_b32 s0, s4, 11
	v_ashrrev_i32_e32 v12, 5, v4
	s_add_i32 s34, s12, s0
	v_ashrrev_i32_e32 v11, 31, v10
	v_ashrrev_i32_e32 v13, 31, v12
	v_lshlrev_b32_e32 v80, 4, v137
	v_lshl_add_u64 v[2:3], v[10:11], 0, s[34:35]
	v_lshl_add_u64 v[4:5], v[12:13], 0, s[34:35]
	v_lshl_add_u64 v[0:1], s[24:25], 0, v[80:81]
	v_lshlrev_b64 v[2:3], 9, v[2:3]
	v_lshlrev_b64 v[4:5], 9, v[4:5]
	v_lshl_add_u64 v[2:3], v[0:1], 0, v[2:3]
	v_lshl_add_u64 v[0:1], v[0:1], 0, v[4:5]
	global_load_dwordx4 v[2:5], v[2:3], off
	s_nop 0
	global_load_dwordx4 v[6:9], v[0:1], off
	v_add_u32_e32 v0, 0, v80
	v_or_b32_e32 v80, s34, v137
	v_lshl_add_u64 v[14:15], v[80:81], 4, s[30:31]
	global_load_dwordx4 v[64:67], v[14:15], off
	v_ashrrev_i32_e32 v1, 5, v136
	v_or_b32_e32 v16, s0, v137
	v_lshlrev_b32_e32 v14, 3, v1
	v_mad_u64_u32 v[10:11], s[0:1], v10, s55, v[0:1]
	s_cmp_le_i32 s62, s61
	v_mad_u64_u32 v[12:13], s[0:1], v12, s55, v[0:1]
	v_lshlrev_b32_e32 v80, 7, v16
	v_ashrrev_i32_e32 v15, 31, v14
	s_cselect_b64 s[0:1], -1, 0
	v_lshl_add_u64 v[16:17], s[26:27], 0, v[80:81]
	s_and_b64 vcc, exec, s[0:1]
	v_lshl_add_u64 v[82:83], v[14:15], 1, v[16:17]
	s_cbranch_vccz .Lidxq_nodma
	s_lshl_b32 s4, s62, 11
	v_mov_b32_e32 v244, s4
	v_ashrrev_i32_e32 v245, 31, v244
	v_lshl_add_u64 v[244:245], v[244:245], 1, v[82:83]
	s_mov_b32 s4, m0
	s_mov_b32 m0, s50
	s_nop 0
	global_load_lds_dwordx4 v[244:245], off
	v_lshl_add_u64 v[246:247], v[244:245], 0, 32
	s_mov_b32 m0, s58
	s_nop 0
	global_load_lds_dwordx4 v[246:247], off
	v_lshl_add_u64 v[246:247], v[244:245], 0, 64
	s_mov_b32 m0, s59
	s_nop 0
	global_load_lds_dwordx4 v[246:247], off
	v_lshl_add_u64 v[244:245], v[244:245], 0, s[36:37]
	s_mov_b32 m0, s60
	s_nop 0
	global_load_lds_dwordx4 v[244:245], off
	s_mov_b32 m0, s4
	s_waitcnt vmcnt(6)
	ds_write_b128 v10, v[2:5]
	s_waitcnt vmcnt(5)
	ds_write_b128 v12, v[6:9]
	s_branch .Lidxq_join
.Lidxq_nodma:
	s_waitcnt vmcnt(2)
	ds_write_b128 v10, v[2:5]
	s_waitcnt vmcnt(1)
	ds_write_b128 v12, v[6:9]
.Lidxq_join:
	s_waitcnt lgkmcnt(0)
	s_barrier
.LBB0_960:
	v_lshlrev_b32_e32 v2, 4, v136
	v_lshlrev_b32_e32 v80, 2, v1
	v_lshl_add_u32 v84, v137, 9, v0
	v_sub_u32_e32 v85, v137, v80
	v_lshl_add_u32 v98, v1, 4, v84
	s_mov_b64 s[4:5], -1
	s_and_b64 vcc, exec, s[0:1]
	v_readfirstlane_b32 s0, v0
	v_add_u32_e32 v103, s49, v2
	s_cbranch_vccz .LBB0_964
	s_waitcnt vmcnt(0)
	ds_read_b128 v[48:51], v103 offset:36864
	ds_read_b128 v[76:79], v103 offset:37888
	ds_read_b128 v[72:75], v103 offset:38912
	ds_read_b128 v[68:71], v103 offset:39936
	s_waitcnt lgkmcnt(0)
	s_add_i32 s0, s62, 8
	s_cmp_gt_i32 s0, s61
	s_cbranch_scc1 .LBB0_963
	s_lshl_b32 s1, s0, 11
	v_mov_b32_e32 v0, s1
	s_nop 0
	v_ashrrev_i32_e32 v1, 31, v0
	v_lshl_add_u64 v[0:1], v[0:1], 1, v[82:83]
	s_mov_b32 s1, m0
	s_mov_b32 m0, s50
	s_nop 0
	global_load_lds_dwordx4 v[0:1], off
	s_mov_b32 m0, s1
	v_lshl_add_u64 v[2:3], v[0:1], 0, 32
	s_mov_b32 s1, m0
	s_mov_b32 m0, s58
	s_nop 0
	global_load_lds_dwordx4 v[2:3], off
	s_mov_b32 m0, s1
	v_lshl_add_u64 v[2:3], v[0:1], 0, 64
	s_mov_b32 s1, m0
	s_mov_b32 m0, s59
	s_nop 0
	global_load_lds_dwordx4 v[2:3], off
	s_mov_b32 m0, s1
	v_lshl_add_u64 v[0:1], v[0:1], 0, s[36:37]
	s_mov_b32 s1, m0
	s_mov_b32 m0, s60
	s_nop 0
	global_load_lds_dwordx4 v[0:1], off
	s_mov_b32 m0, s1
